# P1 tile order rotated per workgroup (start section = bx>>6) so the four epilogue kinds and their store bursts run concurrently
# baseline (speedup 1.0000x reference)
; #define PG8_STAGE(bufoff, gbase, voff) do { _Pragma("unroll") for (int _i = 0; _i < 2; ++_i) \
;         __builtin_amdgcn_global_load_lds((const unsigned*)((const char*)(gbase) + (voff)[_i]), (PG8_LAS unsigned*)(lds + (bufoff) + ldsw + _i * 8192), 16, 0, 0); } while (0)
; #define PG8_BAR __builtin_amdgcn_s_barrier()
;     __host__ __device__ bool next(int i, Unit& u) const {
;         const long L = (long)i * G + c; if (L >= nwg) return false;
;         int wgid = (int)L; { const int q = nwg / NXCD, r = nwg % NXCD, xcd = wgid % NXCD, off = wgid / NXCD; wgid = (xcd < r ? xcd * (q + 1) : r * (q + 1) + (xcd - r) * q) + off; }
;         const int nig = WGM * nN, gid = wgid / nig, fm = gid * WGM, gsz = (nM - fm) < WGM ? (nM - fm) : WGM;
;         u.pm = fm + ((wgid % nig) % gsz); u.pn = (wgid % nig) / gsz; return true;
; template <class Epi, class Sched, bool ALIGN_EPI = false, bool SP2 = false, bool SPLITK = false>
; __device__ __forceinline__ void gemm_phase(PG8_LAS unsigned char* lds, const Gemm g, const Sched& S, const Epi& E) {
;     ...
;     const char* cA = (const char*)g.A + (size_t)cur.pm * tstep; const char* cB = (const char*)g.Bt + (size_t)cur.pn * tstep;
;     const char* cA2 = SPLITK ? (const char*)g.A2 + (size_t)cur.pm * tstep : cA; const char* cB2 = SPLITK ? (const char*)g.Bt2 + (size_t)cur.pn * tstep : cB;
;     ...
;     S.a_ready(cur);
;     if constexpr (SP2) {
;         PG8_STAGE(PG8_SB(0, 0), cB, voffB); PG8_STAGE(PG8_SB(0, 1), cB + hstep, voffB); PG8_STAGE(PG8_SA(0, 0), cA, voffA); PG8_STAGE(PG8_SA(0, 1), cA + hstep, voffA);
;         PG8_STAGE(PG8_SB(1, 0), cB + kstep, voffB); PG8_STAGE(PG8_SA(1, 0), cA + kstep, voffA); PG8_STAGE(PG8_SB(1, 1), cB + hstep + kstep, voffB);
;         if (wr == 1) PG8_BAR;
.LBB0_151:
	s_ashr_i32 s2, s12, 3
	s_add_i32 s2, s17, s2
	s_ashr_i32 s3, s2, 31
	s_lshr_b32 s3, s3, 24
	s_add_i32 s3, s2, s3
	s_ashr_i32 s12, s3, 8
	s_and_b32 s3, s3, 0xff00
	s_sub_i32 s2, s2, s3
	s_sext_i32_i16 s3, s2
	s_bfe_u32 s3, s3, 0x3001c
	s_add_i32 s3, s2, s3
	s_sext_i32_i16 s16, s3
	s_and_b32 s3, s3, 0xfff8
	s_sub_i32 s2, s2, s3
	s_lshl_b32 s12, s12, 3
	s_sext_i32_i16 s2, s2
	s_add_i32 s52, s12, s2
	s_ashr_i32 s42, s16, 3
	s_cmp_lg_u32 s98, 0
	s_cbranch_scc0 .Lrot_skip0
	s_lshr_b32 s2, s1, 6
	s_lshl_b32 s2, s2, 3
	s_add_i32 s42, s42, s2
.Lrot_skip0:
.LBB0_152:
	s_mul_i32 s3, s92, 0x2680000
	v_readlane_b32 s16, v253, 48
	s_mul_hi_u32 s2, s92, 0x2680000
	v_readlane_b32 s17, v253, 49
	s_add_u32 s3, s16, s3
	v_writelane_b32 v255, s3, 45
	s_addc_u32 s2, s17, s2
	v_writelane_b32 v255, s2, 46
	s_and_b64 vcc, exec, s[38:39]
	s_cbranch_vccnz .LBB0_192
	v_ashrrev_i32_e32 v0, 31, v2
	v_lshrrev_b32_e32 v0, 26, v0
	v_add_u32_e32 v0, v2, v0
	v_ashrrev_i32_e32 v3, 6, v0
	v_bfe_i32 v0, v2, 27, 1
	v_lshlrev_b32_e32 v6, 4, v2
	v_lshrrev_b32_e32 v0, 22, v0
	v_add_u32_e32 v0, v6, v0
	v_and_b32_e32 v0, 0xfffffc00, v0
	v_sub_u32_e32 v0, v6, v0
	v_lshrrev_b32_e32 v4, 4, v0
	v_bitop3_b32 v0, v4, v0, 32 bitop3:0x6c
	v_lshlrev_b32_e32 v4, 3, v3
	v_and_b32_e32 v5, -16, v4
	v_ashrrev_i32_e32 v4, 31, v0
	v_lshrrev_b32_e32 v4, 26, v4
	v_add_u32_e32 v7, v0, v4
	v_ashrrev_i32_e32 v4, 6, v7
	v_add_u32_e32 v8, v4, v5
	v_lshlrev_b32_e32 v5, 5, v3
	v_and_b32_e32 v9, 32, v5
	v_and_b32_e32 v5, 0xc0, v7
	v_sub_u32_e32 v0, v0, v5
	v_ashrrev_i16_sdwa v0, v234, sext(v0) dst_sel:DWORD dst_unused:UNUSED_PAD src0_sel:DWORD src1_sel:BYTE_0
	v_bfe_i32 v5, v0, 0, 16
	v_lshlrev_b32_e32 v0, 1, v8
	v_lshrrev_b32_e32 v7, 2, v8
	v_and_b32_e32 v10, 3, v4
	s_mov_b32 s2, 0x1fffe0
	v_and_b32_e32 v0, 24, v0
	v_and_b32_e32 v7, 4, v7
	v_and_or_b32 v10, v8, s2, v10
	v_or3_b32 v0, v10, v7, v0
	v_add_lshl_u32 v7, v9, v5, 1
	v_lshl_add_u32 v168, v8, 11, v7
	v_lshl_add_u32 v0, v0, 11, v7
	v_add_u32_e32 v7, 0x2000, v6
	v_ashrrev_i32_e32 v6, 31, v7
	v_lshrrev_b32_e32 v6, 22, v6
	v_add_u32_e32 v6, v7, v6
	v_ashrrev_i32_e32 v6, 10, v6
	v_mul_i32_i24_e32 v8, 0x400, v6
	v_sub_u32_e32 v7, v7, v8
	v_lshrrev_b32_e32 v8, 4, v7
	v_bitop3_b32 v8, v8, v7, 32 bitop3:0x6c
	v_lshlrev_b32_e32 v7, 3, v6
	v_and_b32_e32 v9, -16, v7
	v_ashrrev_i32_e32 v7, 31, v8
	v_lshrrev_b32_e32 v7, 26, v7
	v_add_u32_e32 v10, v8, v7
	v_ashrrev_i32_e32 v7, 6, v10
	s_ashr_i32 s12, s4, 6
	v_add_u32_e32 v9, v7, v9
	v_and_b32_e32 v13, 3, v7
	s_ashr_i32 s53, s52, 31
	s_ashr_i32 s43, s42, 31
	v_and_b32_e32 v10, 0xc0, v10
	v_and_or_b32 v13, v9, s2, v13
	s_ashr_i32 s20, s4, 8
	s_lshl_b32 s33, s12, 10
	s_lshl_b64 s[2:3], s[52:53], 19
	s_lshl_b64 s[16:17], s[42:43], 19
	v_readlane_b32 s18, v255, 45
	v_sub_u32_e32 v8, v8, v10
	s_add_u32 s46, s18, s16
	v_readlane_b32 s16, v255, 46
	v_lshlrev_b32_e32 v11, 5, v6
	v_ashrrev_i16_sdwa v8, v234, sext(v8) dst_sel:DWORD dst_unused:UNUSED_PAD src0_sel:DWORD src1_sel:BYTE_0
	v_lshlrev_b32_e32 v10, 1, v9
	v_lshrrev_b32_e32 v12, 2, v9
	s_addc_u32 s47, s16, s17
	s_add_i32 s51, s33, 0
	v_and_b32_e32 v11, 32, v11
	v_bfe_i32 v8, v8, 0, 16
	v_and_b32_e32 v10, 24, v10
	v_and_b32_e32 v12, 4, v12
	s_add_i32 m0, s51, 0x10000
	v_or3_b32 v10, v13, v12, v10
	v_add_lshl_u32 v11, v11, v8, 1
	global_load_lds_dwordx4 v0, s[46:47]
	s_add_i32 m0, s51, 0x12000
	v_lshl_add_u32 v172, v10, 11, v11
	s_add_u32 s16, s46, 0x40000
	global_load_lds_dwordx4 v172, s[46:47]
	s_addc_u32 s17, s47, 0
	s_add_i32 m0, s51, 0x14000
	v_lshl_add_u32 v170, v9, 11, v11
	global_load_lds_dwordx4 v0, s[16:17]
	s_add_i32 m0, s51, 0x16000
	s_add_u32 s48, s82, s2
	s_addc_u32 s49, s83, s3
	s_add_i32 s53, s51, 0x2000
	global_load_lds_dwordx4 v172, s[16:17]
	s_mov_b32 m0, s51
	s_add_u32 s2, s48, 0x40000
	global_load_lds_dwordx4 v168, s[48:49]
	s_mov_b32 m0, s53
	s_addc_u32 s3, s49, 0
	s_add_i32 s56, s51, 0x4000
	global_load_lds_dwordx4 v170, s[48:49]
	s_mov_b32 m0, s56
	s_add_i32 s57, s51, 0x6000
	v_lshl_add_u64 v[10:11], s[46:47], 0, v[0:1]
	v_mov_b32_e32 v173, v1
	global_load_lds_dwordx4 v168, s[2:3]
	s_mov_b32 m0, s57
	v_lshl_add_u64 v[12:13], s[46:47], 0, v[172:173]
	v_mov_b32_e32 v169, v1
	global_load_lds_dwordx4 v170, s[2:3]
	s_add_i32 m0, s51, 0x18000
	v_lshl_add_u64 v[10:11], v[10:11], 0, s[70:71]
	v_lshl_add_u64 v[14:15], s[48:49], 0, v[168:169]
	v_mov_b32_e32 v171, v1
	global_load_lds_dwordx4 v[10:11], off
	v_lshl_add_u64 v[10:11], v[12:13], 0, s[70:71]
	s_add_i32 m0, s51, 0x1a000
	s_add_i32 s58, s51, 0x8000
	v_lshl_add_u64 v[16:17], s[48:49], 0, v[170:171]
	global_load_lds_dwordx4 v[10:11], off
	v_lshl_add_u64 v[10:11], v[14:15], 0, s[70:71]
	s_mov_b32 m0, s58
	s_add_i32 s59, s51, 0xa000
	global_load_lds_dwordx4 v[10:11], off
	v_lshl_add_u64 v[10:11], v[16:17], 0, s[70:71]
	s_mov_b32 m0, s59
	s_add_u32 s2, s46, 0x40080
	global_load_lds_dwordx4 v[10:11], off
	s_addc_u32 s3, s47, 0
	s_add_i32 m0, s51, 0x1c000
	s_nop 0
	global_load_lds_dwordx4 v0, s[2:3]
	s_add_i32 m0, s51, 0x1e000
	s_cmp_eq_u32 s20, 1
	global_load_lds_dwordx4 v172, s[2:3]
	s_cselect_b64 s[2:3], -1, 0
	s_cmp_lg_u32 s20, 1
	s_cbranch_scc1 .LBB0_155
	s_barrier

;     __host__ __device__ bool next(int i, Unit& u) const {
;         const long L = (long)i * G + c; if (L >= nwg) return false;
;         int wgid = (int)L; { const int q = nwg / NXCD, r = nwg % NXCD, xcd = wgid % NXCD, off = wgid / NXCD; wgid = (xcd < r ? xcd * (q + 1) : r * (q + 1) + (xcd - r) * q) + off; }
; template <class Epi, class Sched, bool ALIGN_EPI = false, bool SP2 = false, bool SPLITK = false>
; __device__ __forceinline__ void gemm_phase(PG8_LAS unsigned char* lds, const Gemm g, const Sched& S, const Epi& E) {
;     ...
;         const bool has_next = S.next(ui + 1, nxt);
.LBB0_158:
	s_add_i32 s68, s68, 1
	s_mul_i32 s4, s68, s79
	s_mul_hi_u32 s12, s68, s80
	s_add_i32 s12, s12, s4
	s_mul_i32 s4, s68, s80
	s_add_u32 s36, s4, s1
	s_addc_u32 s37, s12, s13
	v_mov_b64_e32 v[2:3], 0x7ff
	v_cmp_gt_i64_e32 vcc, s[36:37], v[2:3]
	v_cmp_lt_i64_e64 s[38:39], s[36:37], v[236:237]
	s_cbranch_vccnz .LBB0_164
	s_cmp_lg_u32 s98, 0
	s_cbranch_scc0 .Lrot_skip1
	s_lshr_b32 s4, s1, 6
	s_lshl_b32 s4, s4, 1
	s_add_i32 s4, s4, s68
	s_and_b32 s4, s4, 7
	s_mul_i32 s4, s4, s80
	s_add_i32 s36, s4, s1
.Lrot_skip1:
	s_ashr_i32 s4, s36, 31
	s_lshr_b32 s4, s4, 29
	s_add_i32 s4, s36, s4
	s_and_b32 s12, s4, -8
	s_sub_i32 s12, s36, s12
	s_cmp_gt_i32 s12, -1
	s_mov_b64 s[20:21], -1
	s_cbranch_scc0 .LBB0_161
	s_lshl_b32 s22, s12, 8
	s_mov_b64 s[20:21], 0
